# base14 + FFT11 item load loop unrolled: 8 loads in flight with counted waits, no store drain before the loads
# speedup vs baseline: 1.0120x; 1.0015x over previous
; #define LAS __attribute__((address_space(3)))
; __device__ __forceinline__ void unpack8(const v4u u, float (&f)[8]) { f[0] = bf2f(u.x & 0xffffu); f[1] = bf2f(u.x >> 16); f[2] = bf2f(u.y & 0xffffu); f[3] = bf2f(u.y >> 16); f[4] = bf2f(u.z & 0xffffu); f[5] = bf2f(u.z >> 16); f[6] = bf2f(u.w & 0xffffu); f[7] = bf2f(u.w >> 16); }
; template <int LOGN, int NCOL>
; __device__ __forceinline__ void fft_items(const Args& a, LAS unsigned char* lds, const WCtx& w, const bf16* VT, float* FO, int rowbase0, float scale) {
;     ...
;         for (int m = j; m < N / 8; m += TPC) {
;             const v4u vr = *(const v4u*)(src + 8 * m), vi = *(const v4u*)(src + N + 8 * m); float f[8];
;             unpack8(vr, f); *(LAS f32x4*)(XR + c * CS + fpad(8 * m)) = (f32x4){f[0], f[1], f[2], f[3]}; *(LAS f32x4*)(XR + c * CS + fpad(8 * m) + 4) = (f32x4){f[4], f[5], f[6], f[7]};
;             unpack8(vi, f); *(LAS f32x4*)(XI + c * CS + fpad(8 * m)) = (f32x4){f[0], f[1], f[2], f[3]}; *(LAS f32x4*)(XI + c * CS + fpad(8 * m) + 4) = (f32x4){f[4], f[5], f[6], f[7]}; }
.LBB0_1001:
	s_lshl_b32 s10, s13, 3
	s_and_saveexec_b64 s[2:3], vcc
	s_cbranch_execz .LBB0_1004
	v_add_u32_e32 v24, s10, v35
	v_ashrrev_i32_e32 v25, 31, v24
	v_readlane_b32 s4, v253, 45
	v_lshlrev_b64 v[24:25], 13, v[24:25]
	v_readlane_b32 s5, v253, 46
	s_mov_b64 s[6:7], 0
	v_mov_b32_e32 v28, v42
	v_lshl_add_u64 v[24:25], s[4:5], 0, v[24:25]
	s_mov_b64 s[4:5], 0x1000
	v_lshl_add_u64 v[26:27], v[24:25], 0, s[4:5]
	v_mov_b32_e32 v30, v41
	v_mov_b32_e32 v31, v36
	v_ashrrev_i32_e32 v29, 31, v28
	v_lshlrev_b64 v[48:49], 1, v[28:29]
	v_lshl_add_u64 v[44:45], v[24:25], 0, v[48:49]
	v_lshl_add_u64 v[48:49], v[26:27], 0, v[48:49]
	global_load_dwordx4 v[100:103], v[44:45], off
	global_load_dwordx4 v[104:107], v[48:49], off
	global_load_dwordx4 v[108:111], v[44:45], off offset:1024
	global_load_dwordx4 v[112:115], v[48:49], off offset:1024
	global_load_dwordx4 v[116:119], v[44:45], off offset:2048
	global_load_dwordx4 v[120:123], v[48:49], off offset:2048
	global_load_dwordx4 v[124:127], v[44:45], off offset:3072
	global_load_dwordx4 v[128:131], v[48:49], off offset:3072
	v_lshlrev_b32_e32 v29, 1, v31
	v_and_b32_e32 v29, 0xffffffe0, v29
	v_add_u32_e32 v29, v30, v29
	v_add_u32_e32 v43, 0xfffef000, v29
	s_waitcnt vmcnt(7)
	v_lshlrev_b32_e32 v56, 16, v100
	v_and_b32_e32 v57, 0xffff0000, v100
	v_lshlrev_b32_e32 v58, 16, v101
	v_and_b32_e32 v59, 0xffff0000, v101
	v_lshlrev_b32_e32 v44, 16, v102
	v_and_b32_e32 v45, 0xffff0000, v102
	v_lshlrev_b32_e32 v46, 16, v103
	v_and_b32_e32 v47, 0xffff0000, v103
	ds_write_b128 v43, v[56:59]
	ds_write_b128 v43, v[44:47] offset:16
	s_waitcnt vmcnt(6)
	v_lshlrev_b32_e32 v52, 16, v104
	v_and_b32_e32 v53, 0xffff0000, v104
	v_lshlrev_b32_e32 v54, 16, v105
	v_and_b32_e32 v55, 0xffff0000, v105
	v_lshlrev_b32_e32 v60, 16, v106
	v_and_b32_e32 v61, 0xffff0000, v106
	v_lshlrev_b32_e32 v62, 16, v107
	v_and_b32_e32 v63, 0xffff0000, v107
	ds_write_b128 v29, v[52:55]
	ds_write_b128 v29, v[60:63] offset:16
	s_waitcnt vmcnt(5)
	v_lshlrev_b32_e32 v68, 16, v108
	v_and_b32_e32 v69, 0xffff0000, v108
	v_lshlrev_b32_e32 v70, 16, v109
	v_and_b32_e32 v71, 0xffff0000, v109
	v_lshlrev_b32_e32 v72, 16, v110
	v_and_b32_e32 v73, 0xffff0000, v110
	v_lshlrev_b32_e32 v74, 16, v111
	v_and_b32_e32 v75, 0xffff0000, v111
	ds_write_b128 v43, v[68:71] offset:2176
	ds_write_b128 v43, v[72:75] offset:2192
	s_waitcnt vmcnt(4)
	v_lshlrev_b32_e32 v76, 16, v112
	v_and_b32_e32 v77, 0xffff0000, v112
	v_lshlrev_b32_e32 v78, 16, v113
	v_and_b32_e32 v79, 0xffff0000, v113
	v_lshlrev_b32_e32 v80, 16, v114
	v_and_b32_e32 v81, 0xffff0000, v114
	v_lshlrev_b32_e32 v82, 16, v115
	v_and_b32_e32 v83, 0xffff0000, v115
	ds_write_b128 v29, v[76:79] offset:2176
	ds_write_b128 v29, v[80:83] offset:2192
	s_waitcnt vmcnt(3)
	v_lshlrev_b32_e32 v56, 16, v116
	v_and_b32_e32 v57, 0xffff0000, v116
	v_lshlrev_b32_e32 v58, 16, v117
	v_and_b32_e32 v59, 0xffff0000, v117
	v_lshlrev_b32_e32 v44, 16, v118
	v_and_b32_e32 v45, 0xffff0000, v118
	v_lshlrev_b32_e32 v46, 16, v119
	v_and_b32_e32 v47, 0xffff0000, v119
	ds_write_b128 v43, v[56:59] offset:4352
	ds_write_b128 v43, v[44:47] offset:4368
	s_waitcnt vmcnt(2)
	v_lshlrev_b32_e32 v52, 16, v120
	v_and_b32_e32 v53, 0xffff0000, v120
	v_lshlrev_b32_e32 v54, 16, v121
	v_and_b32_e32 v55, 0xffff0000, v121
	v_lshlrev_b32_e32 v60, 16, v122
	v_and_b32_e32 v61, 0xffff0000, v122
	v_lshlrev_b32_e32 v62, 16, v123
	v_and_b32_e32 v63, 0xffff0000, v123
	ds_write_b128 v29, v[52:55] offset:4352
	ds_write_b128 v29, v[60:63] offset:4368
	s_waitcnt vmcnt(1)
	v_lshlrev_b32_e32 v68, 16, v124
	v_and_b32_e32 v69, 0xffff0000, v124
	v_lshlrev_b32_e32 v70, 16, v125
	v_and_b32_e32 v71, 0xffff0000, v125
	v_lshlrev_b32_e32 v72, 16, v126
	v_and_b32_e32 v73, 0xffff0000, v126
	v_lshlrev_b32_e32 v74, 16, v127
	v_and_b32_e32 v75, 0xffff0000, v127
	ds_write_b128 v43, v[68:71] offset:6528
	ds_write_b128 v43, v[72:75] offset:6544
	s_waitcnt vmcnt(0)
	v_lshlrev_b32_e32 v76, 16, v128
	v_and_b32_e32 v77, 0xffff0000, v128
	v_lshlrev_b32_e32 v78, 16, v129
	v_and_b32_e32 v79, 0xffff0000, v129
	v_lshlrev_b32_e32 v80, 16, v130
	v_and_b32_e32 v81, 0xffff0000, v130
	v_lshlrev_b32_e32 v82, 16, v131
	v_and_b32_e32 v83, 0xffff0000, v131
	ds_write_b128 v29, v[76:79] offset:6528
	ds_write_b128 v29, v[80:83] offset:6544
	v_add_u32_e32 v30, 0x2000, v30
	v_add_u32_e32 v28, 0x800, v28
	v_add_u32_e32 v29, 0x100, v31
	v_mov_b32_e32 v31, v29
	s_mov_b64 s[4:5], exec
	s_mov_b64 s[6:7], exec
